# attention piece prologue: kmean and Q loads issued before the 15 LDS park writes (park's own lgkmcnt(0) folded into the pre-barrier wait)
# baseline (speedup 1.0000x reference)
; #define LAS __attribute__((address_space(3)))
; __device__ __forceinline__ void phase_moba_attn(const Params& P, LAS unsigned char* lds, int l, int qslot) {
;     ...
;         const unsigned x = y < 128u ? 896u + y : y - 128u;
;         if (tid == 0) nextx = __hip_atomic_fetch_add(qctr, 1u, __ATOMIC_RELAXED, __HIP_MEMORY_SCOPE_AGENT);
;         if (x >= 384u) {
;             if (x < 896u) sgu_item(P, lds, l, (int)(x - 384u));
;             else { const int tile = (int)(x - 896u) * 8 + wave; if (tile < 512) pool_tile(P, l, tile, lane); else conv_tile(P, l, tile - 512, lane); }
;             continue;
;         }
;         const int bh = (int)(x & 15u), rr = (int)(x >> 4);
;         const unsigned ent = (unsigned)((rr < 12 ? (TA >> (5 * rr)) : (TB >> (5 * (rr - 12)))) & 31ull);
;         const int i = (int)(ent & 15u), sp = (int)(ent >> 4);
;         int jlo = 0, jhi = i;
;         if (i >= 8) { const int h1 = (i + 1) >> 1; if (sp == 0) jhi = h1 - 1; else jlo = h1; }
;         const int nch = 4 * (jhi - jlo + 1);
;         const int t0 = 256 * i, tq = t0 + 32 * wave + ln, tql = 32 * wave + ln;
;         { const f32x4 v = *(const f32x4*)(kmean + (size_t)bh * NBLK * HD + 4 * tid); *(LAS f32x4*)(km + 4 * tid) = v; }
;         f16x8 qf[8];
;         { const f16* qrow = Q16 + ((size_t)bh * SEQ + tq) * HD + 8 * hf;
; #pragma unroll
;             for (int st = 0; st < 8; ++st) qf[st] = *(const f16x8*)(qrow + 16 * st); }
;         __syncthreads();
;         unsigned mask = 0u;
;         if (i <= 3) mask = (1u << i) - 1u;
;         else {
;             float v0 = -INFINITY, v1 = -INFINITY, v2 = -INFINITY; int i0 = 0, i1 = 0, i2 = 0;
; #pragma unroll 1
;             for (int j = 0; j < i; ++j) {
.LBB0_893:
	s_or_b64 exec, exec, s[0:1]
	s_cmpk_lt_u32 s2, 0x80
	s_movk_i32 s0, 0x380
	s_cselect_b32 s63, s0, 0xffffff80
	s_add_i32 s63, s63, s2
	s_cmpk_lt_u32 s63, 0x180
	s_mov_b64 s[0:1], -1
	s_cbranch_scc0 .LBB0_925
	s_and_b32 s19, s2, 15
	s_lshr_b32 s2, s63, 4
	s_cmpk_lt_u32 s63, 0xc0
	s_mul_i32 s2, s2, 5
	s_cselect_b64 s[0:1], -1, 0
	s_sub_i32 s3, s2, 60
	s_and_b64 s[0:1], s[0:1], exec
	s_mov_b32 s0, 0xdad86e7
	s_cselect_b32 s1, s0, 0x44341
	s_mov_b32 s0, 0x5ae3fbef
	s_cselect_b32 s2, s2, s3
	s_cselect_b32 s0, s0, 0x3194a8ba
	s_lshl_b32 s56, s19, 13
	v_lshl_add_u64 v[4:5], v[162:163], 0, s[56:57]
	global_load_dwordx4 v[4:7], v[4:5], off
	s_lshr_b64 s[8:9], s[0:1], s2
	s_and_b32 s3, s8, 15
	s_lshl_b32 s2, s3, 8
	v_add_u32_e32 v8, s2, v219
	s_lshl_b32 s0, s19, 12
	s_mov_b32 s1, s57
	v_ashrrev_i32_e32 v9, 31, v8
	v_lshl_add_u64 v[214:215], s[0:1], 0, v[8:9]
	s_mov_b64 s[12:13], -1
	s_cmp_lt_u32 s3, 4
	v_lshlrev_b64 v[8:9], 8, v[214:215]
	v_lshl_add_u64 v[8:9], v[166:167], 0, v[8:9]
	global_load_dwordx4 v[98:101], v[8:9], off
	global_load_dwordx4 v[102:105], v[8:9], off offset:32
	global_load_dwordx4 v[106:109], v[8:9], off offset:64
	global_load_dwordx4 v[110:113], v[8:9], off offset:96
	global_load_dwordx4 v[114:117], v[8:9], off offset:128
	global_load_dwordx4 v[118:121], v[8:9], off offset:160
	global_load_dwordx4 v[122:125], v[8:9], off offset:192
	global_load_dwordx4 v[126:129], v[8:9], off offset:224
	v_mov_b32_e32 v245, 0x14000
	v_lshl_add_u32 v245, v0, 2, v245
	ds_write_b32 v245, v192 offset:0
	ds_write_b32 v245, v193 offset:2048
	ds_write_b32 v245, v194 offset:4096
	ds_write_b32 v245, v195 offset:6144
	ds_write_b32 v245, v196 offset:8192
	ds_write_b32 v245, v197 offset:10240
	ds_write_b32 v245, v198 offset:12288
	ds_write_b32 v245, v199 offset:14336
	ds_write_b32 v245, v200 offset:16384
	ds_write_b32 v245, v201 offset:18432
	ds_write_b32 v245, v202 offset:20480
	ds_write_b32 v245, v203 offset:22528
	ds_write_b32 v245, v204 offset:24576
	ds_write_b32 v245, v205 offset:26624
	ds_write_b32 v245, v206 offset:28672
	s_waitcnt vmcnt(8)
	ds_write_b128 v220, v[4:7]
	s_waitcnt lgkmcnt(0)
	s_barrier
	s_cbranch_scc1 .LBB0_905
	v_and_b32_e32 v4, 64, v238
	v_xor_b32_e32 v2, 32, v238
	v_add_u32_e32 v4, 64, v4
	v_cmp_lt_i32_e32 vcc, v2, v4
	s_waitcnt vmcnt(7)
	v_cvt_f32_f16_e32 v4, v98
	v_cvt_f32_f16_sdwa v5, v98 dst_sel:DWORD dst_unused:UNUSED_PAD src0_sel:WORD_1
	v_cvt_f32_f16_e32 v6, v99
	v_cvt_f32_f16_sdwa v7, v99 dst_sel:DWORD dst_unused:UNUSED_PAD src0_sel:WORD_1
	v_cvt_f32_f16_e32 v8, v100
	v_cvt_f32_f16_sdwa v9, v100 dst_sel:DWORD dst_unused:UNUSED_PAD src0_sel:WORD_1
	v_cvt_f32_f16_e32 v10, v101
	v_cvt_f32_f16_sdwa v11, v101 dst_sel:DWORD dst_unused:UNUSED_PAD src0_sel:WORD_1
	s_waitcnt vmcnt(6)
	v_cvt_f32_f16_e32 v12, v102
	v_cvt_f32_f16_sdwa v13, v102 dst_sel:DWORD dst_unused:UNUSED_PAD src0_sel:WORD_1
	v_cvt_f32_f16_e32 v14, v103
	v_cvt_f32_f16_sdwa v15, v103 dst_sel:DWORD dst_unused:UNUSED_PAD src0_sel:WORD_1
	v_cvt_f32_f16_e32 v16, v104
	v_cvt_f32_f16_sdwa v17, v104 dst_sel:DWORD dst_unused:UNUSED_PAD src0_sel:WORD_1
	v_cvt_f32_f16_e32 v18, v105
	v_cvt_f32_f16_sdwa v19, v105 dst_sel:DWORD dst_unused:UNUSED_PAD src0_sel:WORD_1
	s_waitcnt vmcnt(5)
	v_cvt_f32_f16_e32 v20, v106
	v_cvt_f32_f16_sdwa v21, v106 dst_sel:DWORD dst_unused:UNUSED_PAD src0_sel:WORD_1
	v_cvt_f32_f16_e32 v22, v107
	v_cvt_f32_f16_sdwa v23, v107 dst_sel:DWORD dst_unused:UNUSED_PAD src0_sel:WORD_1
	v_cvt_f32_f16_e32 v24, v108
	v_cvt_f32_f16_sdwa v25, v108 dst_sel:DWORD dst_unused:UNUSED_PAD src0_sel:WORD_1
	v_cvt_f32_f16_e32 v26, v109
	v_cvt_f32_f16_sdwa v27, v109 dst_sel:DWORD dst_unused:UNUSED_PAD src0_sel:WORD_1
	s_waitcnt vmcnt(4)
	v_cvt_f32_f16_e32 v28, v110
	v_cvt_f32_f16_sdwa v29, v110 dst_sel:DWORD dst_unused:UNUSED_PAD src0_sel:WORD_1
	v_cvt_f32_f16_e32 v30, v111
	v_cvt_f32_f16_sdwa v31, v111 dst_sel:DWORD dst_unused:UNUSED_PAD src0_sel:WORD_1
	v_cvt_f32_f16_e32 v32, v112
	v_cvt_f32_f16_sdwa v33, v112 dst_sel:DWORD dst_unused:UNUSED_PAD src0_sel:WORD_1
	v_cvt_f32_f16_e32 v34, v113
	v_cvt_f32_f16_sdwa v35, v113 dst_sel:DWORD dst_unused:UNUSED_PAD src0_sel:WORD_1
	s_waitcnt vmcnt(3)
	v_cvt_f32_f16_e32 v36, v114
	v_cvt_f32_f16_sdwa v37, v114 dst_sel:DWORD dst_unused:UNUSED_PAD src0_sel:WORD_1
	v_cvt_f32_f16_e32 v38, v115
	v_cvt_f32_f16_sdwa v39, v115 dst_sel:DWORD dst_unused:UNUSED_PAD src0_sel:WORD_1
	v_cvt_f32_f16_e32 v40, v116
	v_cvt_f32_f16_sdwa v41, v116 dst_sel:DWORD dst_unused:UNUSED_PAD src0_sel:WORD_1
	v_cvt_f32_f16_e32 v42, v117
	v_cvt_f32_f16_sdwa v43, v117 dst_sel:DWORD dst_unused:UNUSED_PAD src0_sel:WORD_1
	s_waitcnt vmcnt(2)
	v_cvt_f32_f16_e32 v44, v118
	v_cvt_f32_f16_sdwa v45, v118 dst_sel:DWORD dst_unused:UNUSED_PAD src0_sel:WORD_1
	v_cvt_f32_f16_e32 v46, v119
	v_cvt_f32_f16_sdwa v47, v119 dst_sel:DWORD dst_unused:UNUSED_PAD src0_sel:WORD_1
	v_cvt_f32_f16_e32 v48, v120
	v_cvt_f32_f16_sdwa v49, v120 dst_sel:DWORD dst_unused:UNUSED_PAD src0_sel:WORD_1
	v_cvt_f32_f16_e32 v50, v121
	v_cvt_f32_f16_sdwa v51, v121 dst_sel:DWORD dst_unused:UNUSED_PAD src0_sel:WORD_1
	s_waitcnt vmcnt(1)
	v_cvt_f32_f16_e32 v52, v122
	v_cvt_f32_f16_sdwa v53, v122 dst_sel:DWORD dst_unused:UNUSED_PAD src0_sel:WORD_1
	v_cvt_f32_f16_e32 v54, v123
	v_cvt_f32_f16_sdwa v55, v123 dst_sel:DWORD dst_unused:UNUSED_PAD src0_sel:WORD_1
	v_cvt_f32_f16_e32 v56, v124
	v_cvt_f32_f16_sdwa v57, v124 dst_sel:DWORD dst_unused:UNUSED_PAD src0_sel:WORD_1
	v_cvt_f32_f16_e32 v58, v125
	v_cvt_f32_f16_sdwa v59, v125 dst_sel:DWORD dst_unused:UNUSED_PAD src0_sel:WORD_1
	s_waitcnt vmcnt(0)
	v_cvt_f32_f16_e32 v60, v126
	v_cvt_f32_f16_sdwa v61, v126 dst_sel:DWORD dst_unused:UNUSED_PAD src0_sel:WORD_1
	v_cvt_f32_f16_e32 v62, v127
	v_cvt_f32_f16_sdwa v63, v127 dst_sel:DWORD dst_unused:UNUSED_PAD src0_sel:WORD_1
	v_cvt_f32_f16_e32 v64, v128
	v_cvt_f32_f16_sdwa v65, v128 dst_sel:DWORD dst_unused:UNUSED_PAD src0_sel:WORD_1
	v_cvt_f32_f16_e32 v66, v129
	v_cvt_f32_f16_sdwa v67, v129 dst_sel:DWORD dst_unused:UNUSED_PAD src0_sel:WORD_1
	v_cndmask_b32_e32 v2, v238, v2, vcc
	s_mov_b32 s1, 0
	v_lshlrev_b32_e32 v2, 2, v2
	s_lshl_b32 s9, s3, 9
	v_mov_b32_e32 v69, 0xff800000
	v_mov_b32_e32 v71, 0
	v_mov_b32_e32 v68, 0
	v_mov_b32_e32 v72, 0
	v_mov_b32_e32 v70, 0xff800000
	v_mov_b32_e32 v73, 0xff800000
	s_mov_b32 s18, 0
